# partial-counter gather skipped on the up-GEMM path of the GEMM-side wait (on the one-counter-per-line layout)
# speedup vs baseline: 1.0001x; 1.0001x over previous
.LBB0_388:
	s_or_b64 exec, exec, s[4:5]
	s_cmp_eq_u32 s51, 1
	s_mov_b64 s[4:5], -1
	s_waitcnt lgkmcnt(0)
	s_barrier
	s_cmp_lg_u32 s86, 0
	s_cbranch_scc1 .Lhf_done
	s_load_dwordx2 s[6:7], s[66:67], 0x100
	v_mov_b32_e32 v0, 0x2017c
	ds_read_b32 v2, v0
	v_readlane_b32 s0, v255, 0
	s_nop 3
	s_and_b32 s1, s0, 7
	s_lshr_b32 s2, s0, 3
	s_cmp_eq_u32 s51, 1
	s_cbranch_scc1 .Lhf_in
	s_mul_i32 s3, s1, 88
	s_add_i32 s3, s3, s2
	s_mul_i32 s8, s3, 0x5d18
	s_lshr_b32 s8, s8, 22
	s_mul_i32 s14, s8, 0xb0
	s_sub_i32 s14, s3, s14
	s_and_b32 s14, s14, 7
	s_lshl_b32 s8, s8, 3
	s_add_i32 s8, s8, s14
	s_add_i32 s15, s3, 32
	s_mul_i32 s9, s15, 0x5d18
	s_lshr_b32 s9, s9, 22
	s_mul_i32 s14, s9, 0xb0
	s_sub_i32 s14, s15, s14
	s_and_b32 s14, s14, 7
	s_lshl_b32 s9, s9, 3
	s_add_i32 s9, s9, s14
	s_add_i32 s15, s3, 64
	s_cmp_lt_u32 s0, 0xc0
	s_cselect_b32 s15, s15, s3
	s_mul_i32 s10, s15, 0x5d18
	s_lshr_b32 s10, s10, 22
	s_mul_i32 s14, s10, 0xb0
	s_sub_i32 s14, s15, s14
	s_and_b32 s14, s14, 7
	s_lshl_b32 s10, s10, 3
	s_add_i32 s10, s10, s14
	v_mov_b32_e32 v9, 0
	s_mov_b32 s11, 0
	s_branch .Lhf_poll
